# FFN-in GEMM main loop: LDS-DMA staging loads issued before the fragment ds_reads in each load segment
# speedup vs baseline: 1.0120x; 1.0120x over previous
.LBB0_684:
	s_add_u32 s22, s20, 0xfffc0080
	s_addc_u32 s23, s21, -1
	s_add_i32 s51, 0, 0x10000
	s_cmp_eq_u32 s50, 12
	s_cselect_b32 s25, s15, s23
	s_cselect_b32 s24, s43, s22
	s_cselect_b32 s23, s13, s49
	s_cselect_b32 s22, s47, s48
	s_add_i32 s54, 0, 0x14000
	v_lshl_add_u64 v[140:141], s[20:21], 0, v[136:137]
	s_add_i32 m0, s36, 0xc000
	s_nop 0
	global_load_lds_dwordx4 v[140:141], off
	v_lshl_add_u64 v[140:141], s[20:21], 0, v[138:139]
	s_add_i32 m0, s36, 0xe000
	s_nop 0
	global_load_lds_dwordx4 v[140:141], off
	v_add_u32_e32 v140, s51, v143
	ds_read_b128 v[146:149], v140
	ds_read_b128 v[150:153], v140 offset:1024
	ds_read_b128 v[154:157], v140 offset:2048
	ds_read_b128 v[158:161], v140 offset:3072
	v_add_u32_e32 v140, s54, v143
	ds_read_b128 v[166:169], v140
	ds_read_b128 v[170:173], v140 offset:1024
	ds_read_b128 v[174:177], v140 offset:2048
	ds_read_b128 v[178:181], v140 offset:3072
	ds_read_b128 v[182:185], v145
	ds_read_b128 v[186:189], v145 offset:1024
	ds_read_b128 v[190:193], v145 offset:2048
	ds_read_b128 v[194:197], v145 offset:3072
	ds_read_b128 v[198:201], v145 offset:4096
	ds_read_b128 v[210:213], v145 offset:5120
	ds_read_b128 v[214:217], v145 offset:6144
	ds_read_b128 v[218:221], v145 offset:7168
	s_waitcnt vmcnt(8)
	s_waitcnt lgkmcnt(0)
	s_barrier
	s_setprio 1
	s_waitcnt lgkmcnt(0)
	v_mfma_f32_16x16x32_bf16 v[126:129], v[146:149], v[182:185], v[126:129]
	v_mfma_f32_16x16x32_bf16 v[118:121], v[154:157], v[182:185], v[118:121]
	v_mfma_f32_16x16x32_bf16 v[110:113], v[146:149], v[190:193], v[110:113]
	v_mfma_f32_16x16x32_bf16 v[102:105], v[154:157], v[190:193], v[102:105]
	v_mfma_f32_16x16x32_bf16 v[94:97], v[146:149], v[198:201], v[94:97]
	v_mfma_f32_16x16x32_bf16 v[86:89], v[154:157], v[198:201], v[86:89]
	v_mfma_f32_16x16x32_bf16 v[78:81], v[146:149], v[214:217], v[78:81]
	v_mfma_f32_16x16x32_bf16 v[70:73], v[154:157], v[214:217], v[70:73]
	v_mfma_f32_16x16x32_bf16 v[126:129], v[150:153], v[186:189], v[126:129]
	v_mfma_f32_16x16x32_bf16 v[118:121], v[158:161], v[186:189], v[118:121]
	v_mfma_f32_16x16x32_bf16 v[110:113], v[150:153], v[194:197], v[110:113]
	v_mfma_f32_16x16x32_bf16 v[102:105], v[158:161], v[194:197], v[102:105]
	v_mfma_f32_16x16x32_bf16 v[94:97], v[150:153], v[210:213], v[94:97]
	v_mfma_f32_16x16x32_bf16 v[86:89], v[158:161], v[210:213], v[86:89]
	v_mfma_f32_16x16x32_bf16 v[78:81], v[150:153], v[218:221], v[78:81]
	v_mfma_f32_16x16x32_bf16 v[70:73], v[158:161], v[218:221], v[70:73]
	s_setprio 0
	s_setprio 1
	v_mfma_f32_16x16x32_bf16 v[122:125], v[166:169], v[182:185], v[122:125]
	v_mfma_f32_16x16x32_bf16 v[114:117], v[174:177], v[182:185], v[114:117]
	v_mfma_f32_16x16x32_bf16 v[106:109], v[166:169], v[190:193], v[106:109]
	v_mfma_f32_16x16x32_bf16 v[98:101], v[174:177], v[190:193], v[98:101]
	v_mfma_f32_16x16x32_bf16 v[90:93], v[166:169], v[198:201], v[90:93]
	v_mfma_f32_16x16x32_bf16 v[82:85], v[174:177], v[198:201], v[82:85]
	v_mfma_f32_16x16x32_bf16 v[74:77], v[166:169], v[214:217], v[74:77]
	v_mfma_f32_16x16x32_bf16 v[66:69], v[174:177], v[214:217], v[66:69]
	v_mfma_f32_16x16x32_bf16 v[122:125], v[170:173], v[186:189], v[122:125]
	v_mfma_f32_16x16x32_bf16 v[114:117], v[178:181], v[186:189], v[114:117]
	v_mfma_f32_16x16x32_bf16 v[106:109], v[170:173], v[194:197], v[106:109]
	v_mfma_f32_16x16x32_bf16 v[98:101], v[178:181], v[194:197], v[98:101]
	v_mfma_f32_16x16x32_bf16 v[90:93], v[170:173], v[210:213], v[90:93]
	v_mfma_f32_16x16x32_bf16 v[82:85], v[178:181], v[210:213], v[82:85]
	v_mfma_f32_16x16x32_bf16 v[74:77], v[170:173], v[218:221], v[74:77]
	v_mfma_f32_16x16x32_bf16 v[66:69], v[178:181], v[218:221], v[66:69]
	s_setprio 0
	s_barrier
	s_add_i32 s51, s51, s29
	v_lshl_add_u64 v[140:141], s[22:23], 0, v[0:1]
	s_mov_b32 m0, s51
	s_nop 0
	global_load_lds_dwordx4 v[140:141], off
	s_add_i32 m0, s51, 0x2000
	s_add_u32 s52, s22, 0x40000
	v_lshl_add_u64 v[202:203], s[22:23], 0, v[130:131]
	s_addc_u32 s53, s23, 0
	s_add_i32 s51, s54, s29
	global_load_lds_dwordx4 v[202:203], off
	v_lshl_add_u64 v[206:207], s[52:53], 0, v[0:1]
	s_mov_b32 m0, s51
	v_lshl_add_u64 v[222:223], s[24:25], 0, v[132:133]
	global_load_lds_dwordx4 v[206:207], off
	v_lshl_add_u64 v[206:207], s[52:53], 0, v[130:131]
	s_add_i32 m0, s51, 0x2000
	s_nop 0
	global_load_lds_dwordx4 v[206:207], off
	v_lshl_add_u64 v[206:207], s[24:25], 0, v[134:135]
	s_mov_b32 m0, s36
	s_nop 0
	global_load_lds_dwordx4 v[206:207], off
	s_mov_b32 m0, s37
	s_nop 0
	global_load_lds_dwordx4 v[222:223], off
	ds_read_b128 v[182:185], v145 offset:16384
	ds_read_b128 v[186:189], v145 offset:17408
	ds_read_b128 v[190:193], v145 offset:18432
	ds_read_b128 v[194:197], v145 offset:19456
	ds_read_b128 v[198:201], v145 offset:20480
	ds_read_b128 v[210:213], v145 offset:21504
	ds_read_b128 v[214:217], v145 offset:22528
	ds_read_b128 v[218:221], v145 offset:23552
	s_waitcnt vmcnt(8)
	s_waitcnt lgkmcnt(0)
	s_barrier
	s_setprio 1
	s_waitcnt lgkmcnt(0)
	v_mfma_f32_16x16x32_bf16 v[62:65], v[146:149], v[182:185], v[62:65]
	v_mfma_f32_16x16x32_bf16 v[54:57], v[154:157], v[182:185], v[54:57]
	v_mfma_f32_16x16x32_bf16 v[46:49], v[146:149], v[190:193], v[46:49]
	v_mfma_f32_16x16x32_bf16 v[38:41], v[154:157], v[190:193], v[38:41]
	v_mfma_f32_16x16x32_bf16 v[30:33], v[146:149], v[198:201], v[30:33]
	v_mfma_f32_16x16x32_bf16 v[22:25], v[154:157], v[198:201], v[22:25]
	v_mfma_f32_16x16x32_bf16 v[14:17], v[146:149], v[214:217], v[14:17]
	v_mfma_f32_16x16x32_bf16 v[6:9], v[154:157], v[214:217], v[6:9]
	v_mfma_f32_16x16x32_bf16 v[62:65], v[150:153], v[186:189], v[62:65]
	v_mfma_f32_16x16x32_bf16 v[54:57], v[158:161], v[186:189], v[54:57]
	v_mfma_f32_16x16x32_bf16 v[46:49], v[150:153], v[194:197], v[46:49]
	v_mfma_f32_16x16x32_bf16 v[38:41], v[158:161], v[194:197], v[38:41]
	v_mfma_f32_16x16x32_bf16 v[30:33], v[150:153], v[210:213], v[30:33]
	v_mfma_f32_16x16x32_bf16 v[22:25], v[158:161], v[210:213], v[22:25]
	v_mfma_f32_16x16x32_bf16 v[14:17], v[150:153], v[218:221], v[14:17]
	v_mfma_f32_16x16x32_bf16 v[6:9], v[158:161], v[218:221], v[6:9]
	s_setprio 0
	s_setprio 1
	v_mfma_f32_16x16x32_bf16 v[58:61], v[166:169], v[182:185], v[58:61]
	v_mfma_f32_16x16x32_bf16 v[50:53], v[174:177], v[182:185], v[50:53]
	v_mfma_f32_16x16x32_bf16 v[42:45], v[166:169], v[190:193], v[42:45]
	v_mfma_f32_16x16x32_bf16 v[34:37], v[174:177], v[190:193], v[34:37]
	v_mfma_f32_16x16x32_bf16 v[26:29], v[166:169], v[198:201], v[26:29]
	v_mfma_f32_16x16x32_bf16 v[18:21], v[174:177], v[198:201], v[18:21]
	v_mfma_f32_16x16x32_bf16 v[10:13], v[166:169], v[214:217], v[10:13]
	v_mfma_f32_16x16x32_bf16 v[2:5], v[174:177], v[214:217], v[2:5]
	v_mfma_f32_16x16x32_bf16 v[58:61], v[170:173], v[186:189], v[58:61]
	v_mfma_f32_16x16x32_bf16 v[50:53], v[178:181], v[186:189], v[50:53]
	v_mfma_f32_16x16x32_bf16 v[42:45], v[170:173], v[194:197], v[42:45]
	v_mfma_f32_16x16x32_bf16 v[34:37], v[178:181], v[194:197], v[34:37]
	v_mfma_f32_16x16x32_bf16 v[26:29], v[170:173], v[210:213], v[26:29]
	v_mfma_f32_16x16x32_bf16 v[18:21], v[178:181], v[210:213], v[18:21]
	v_mfma_f32_16x16x32_bf16 v[10:13], v[170:173], v[218:221], v[10:13]
	v_mfma_f32_16x16x32_bf16 v[2:5], v[178:181], v[218:221], v[2:5]
	s_setprio 0
	s_barrier
	s_add_i32 s51, 0, 0x18000
	s_add_i32 s52, 0, 0x1c000
	s_add_u32 s24, s24, 0x40000
	s_addc_u32 s25, s25, 0
	s_mov_b32 m0, s38
	v_lshl_add_u64 v[224:225], s[24:25], 0, v[134:135]
	global_load_lds_dwordx4 v[224:225], off
	v_lshl_add_u64 v[224:225], s[24:25], 0, v[132:133]
	s_mov_b32 m0, s39
	s_nop 0
	global_load_lds_dwordx4 v[224:225], off
	v_add_u32_e32 v158, s51, v143
	v_add_u32_e32 v178, s52, v143
	ds_read_b128 v[146:149], v158
	ds_read_b128 v[150:153], v158 offset:1024
	ds_read_b128 v[154:157], v158 offset:2048
	ds_read_b128 v[158:161], v158 offset:3072
	ds_read_b128 v[166:169], v178
	ds_read_b128 v[170:173], v178 offset:1024
	ds_read_b128 v[174:177], v178 offset:2048
	ds_read_b128 v[178:181], v178 offset:3072
	ds_read_b128 v[182:185], v145 offset:32768
	ds_read_b128 v[186:189], v145 offset:33792
	ds_read_b128 v[190:193], v145 offset:34816
	ds_read_b128 v[194:197], v145 offset:35840
	ds_read_b128 v[198:201], v145 offset:36864
	ds_read_b128 v[210:213], v145 offset:37888
	ds_read_b128 v[214:217], v145 offset:38912
	ds_read_b128 v[218:221], v145 offset:39936
	s_waitcnt vmcnt(8)
	s_waitcnt lgkmcnt(0)
	s_barrier
	s_setprio 1
	s_waitcnt lgkmcnt(0)
	v_mfma_f32_16x16x32_bf16 v[126:129], v[146:149], v[182:185], v[126:129]
	v_mfma_f32_16x16x32_bf16 v[118:121], v[154:157], v[182:185], v[118:121]
	v_mfma_f32_16x16x32_bf16 v[110:113], v[146:149], v[190:193], v[110:113]
	v_mfma_f32_16x16x32_bf16 v[102:105], v[154:157], v[190:193], v[102:105]
	v_mfma_f32_16x16x32_bf16 v[94:97], v[146:149], v[198:201], v[94:97]
	v_mfma_f32_16x16x32_bf16 v[86:89], v[154:157], v[198:201], v[86:89]
	v_mfma_f32_16x16x32_bf16 v[78:81], v[146:149], v[214:217], v[78:81]
	v_mfma_f32_16x16x32_bf16 v[70:73], v[154:157], v[214:217], v[70:73]
	v_mfma_f32_16x16x32_bf16 v[126:129], v[150:153], v[186:189], v[126:129]
	v_mfma_f32_16x16x32_bf16 v[118:121], v[158:161], v[186:189], v[118:121]
	v_mfma_f32_16x16x32_bf16 v[110:113], v[150:153], v[194:197], v[110:113]
	v_mfma_f32_16x16x32_bf16 v[102:105], v[158:161], v[194:197], v[102:105]
	v_mfma_f32_16x16x32_bf16 v[94:97], v[150:153], v[210:213], v[94:97]
	v_mfma_f32_16x16x32_bf16 v[86:89], v[158:161], v[210:213], v[86:89]
	v_mfma_f32_16x16x32_bf16 v[78:81], v[150:153], v[218:221], v[78:81]
	v_mfma_f32_16x16x32_bf16 v[70:73], v[158:161], v[218:221], v[70:73]
	s_setprio 0
	s_setprio 1
	v_mfma_f32_16x16x32_bf16 v[122:125], v[166:169], v[182:185], v[122:125]
	v_mfma_f32_16x16x32_bf16 v[114:117], v[174:177], v[182:185], v[114:117]
	v_mfma_f32_16x16x32_bf16 v[106:109], v[166:169], v[190:193], v[106:109]
	v_mfma_f32_16x16x32_bf16 v[98:101], v[174:177], v[190:193], v[98:101]
	v_mfma_f32_16x16x32_bf16 v[90:93], v[166:169], v[198:201], v[90:93]
	v_mfma_f32_16x16x32_bf16 v[82:85], v[174:177], v[198:201], v[82:85]
	v_mfma_f32_16x16x32_bf16 v[74:77], v[166:169], v[214:217], v[74:77]
	v_mfma_f32_16x16x32_bf16 v[66:69], v[174:177], v[214:217], v[66:69]
	v_mfma_f32_16x16x32_bf16 v[122:125], v[170:173], v[186:189], v[122:125]
	v_mfma_f32_16x16x32_bf16 v[114:117], v[178:181], v[186:189], v[114:117]
	v_mfma_f32_16x16x32_bf16 v[106:109], v[170:173], v[194:197], v[106:109]
	v_mfma_f32_16x16x32_bf16 v[98:101], v[178:181], v[194:197], v[98:101]
	v_mfma_f32_16x16x32_bf16 v[90:93], v[170:173], v[210:213], v[90:93]
	v_mfma_f32_16x16x32_bf16 v[82:85], v[178:181], v[210:213], v[82:85]
	v_mfma_f32_16x16x32_bf16 v[74:77], v[170:173], v[218:221], v[74:77]
	v_mfma_f32_16x16x32_bf16 v[66:69], v[178:181], v[218:221], v[66:69]
	s_setprio 0
	s_barrier
	s_add_i32 s24, s51, s29
	v_lshl_add_u64 v[140:141], v[140:141], 0, s[4:5]
	s_mov_b32 m0, s24
	s_nop 0
	global_load_lds_dwordx4 v[140:141], off
	s_add_i32 m0, s24, 0x2000
	s_add_u32 s22, s22, 0x40080
	v_lshl_add_u64 v[140:141], v[202:203], 0, s[4:5]
	s_addc_u32 s23, s23, 0
	s_add_i32 s24, s52, s29
	global_load_lds_dwordx4 v[140:141], off
	v_lshl_add_u64 v[140:141], s[22:23], 0, v[0:1]
	s_mov_b32 m0, s24
	s_nop 0
	global_load_lds_dwordx4 v[140:141], off
	v_lshl_add_u64 v[140:141], s[22:23], 0, v[130:131]
	s_add_i32 m0, s24, 0x2000
	s_nop 0
	global_load_lds_dwordx4 v[140:141], off
	v_lshl_add_u64 v[140:141], v[206:207], 0, s[4:5]
	s_mov_b32 m0, s40
	s_nop 0
	global_load_lds_dwordx4 v[140:141], off
	v_lshl_add_u64 v[140:141], v[222:223], 0, s[4:5]
	s_mov_b32 m0, s41
	s_nop 0
	global_load_lds_dwordx4 v[140:141], off
	ds_read_b128 v[182:185], v145 offset:49152
	ds_read_b128 v[186:189], v145 offset:50176
	ds_read_b128 v[190:193], v145 offset:51200
	ds_read_b128 v[194:197], v145 offset:52224
	ds_read_b128 v[198:201], v145 offset:53248
	ds_read_b128 v[210:213], v145 offset:54272
	ds_read_b128 v[214:217], v145 offset:55296
	ds_read_b128 v[218:221], v145 offset:56320
	s_waitcnt vmcnt(8)
	s_waitcnt lgkmcnt(0)
	s_barrier
	s_setprio 1
	s_waitcnt lgkmcnt(0)
	v_mfma_f32_16x16x32_bf16 v[62:65], v[146:149], v[182:185], v[62:65]
	v_mfma_f32_16x16x32_bf16 v[54:57], v[154:157], v[182:185], v[54:57]
	v_mfma_f32_16x16x32_bf16 v[46:49], v[146:149], v[190:193], v[46:49]
	v_mfma_f32_16x16x32_bf16 v[38:41], v[154:157], v[190:193], v[38:41]
	v_mfma_f32_16x16x32_bf16 v[30:33], v[146:149], v[198:201], v[30:33]
	v_mfma_f32_16x16x32_bf16 v[22:25], v[154:157], v[198:201], v[22:25]
	v_mfma_f32_16x16x32_bf16 v[14:17], v[146:149], v[214:217], v[14:17]
	v_mfma_f32_16x16x32_bf16 v[6:9], v[154:157], v[214:217], v[6:9]
	v_mfma_f32_16x16x32_bf16 v[62:65], v[150:153], v[186:189], v[62:65]
	v_mfma_f32_16x16x32_bf16 v[54:57], v[158:161], v[186:189], v[54:57]
	v_mfma_f32_16x16x32_bf16 v[46:49], v[150:153], v[194:197], v[46:49]
	v_mfma_f32_16x16x32_bf16 v[38:41], v[158:161], v[194:197], v[38:41]
	v_mfma_f32_16x16x32_bf16 v[30:33], v[150:153], v[210:213], v[30:33]
	v_mfma_f32_16x16x32_bf16 v[22:25], v[158:161], v[210:213], v[22:25]
	v_mfma_f32_16x16x32_bf16 v[14:17], v[150:153], v[218:221], v[14:17]
	v_mfma_f32_16x16x32_bf16 v[6:9], v[158:161], v[218:221], v[6:9]
	s_setprio 0
	s_setprio 1
	v_mfma_f32_16x16x32_bf16 v[58:61], v[166:169], v[182:185], v[58:61]
	v_mfma_f32_16x16x32_bf16 v[50:53], v[174:177], v[182:185], v[50:53]
	v_mfma_f32_16x16x32_bf16 v[42:45], v[166:169], v[190:193], v[42:45]
	v_mfma_f32_16x16x32_bf16 v[34:37], v[174:177], v[190:193], v[34:37]
	v_mfma_f32_16x16x32_bf16 v[26:29], v[166:169], v[198:201], v[26:29]
	v_mfma_f32_16x16x32_bf16 v[18:21], v[174:177], v[198:201], v[18:21]
	v_mfma_f32_16x16x32_bf16 v[10:13], v[166:169], v[214:217], v[10:13]
	v_mfma_f32_16x16x32_bf16 v[2:5], v[174:177], v[214:217], v[2:5]
	v_mfma_f32_16x16x32_bf16 v[58:61], v[170:173], v[186:189], v[58:61]
	v_mfma_f32_16x16x32_bf16 v[50:53], v[178:181], v[186:189], v[50:53]
	v_mfma_f32_16x16x32_bf16 v[42:45], v[170:173], v[194:197], v[42:45]
	v_mfma_f32_16x16x32_bf16 v[34:37], v[178:181], v[194:197], v[34:37]
	v_mfma_f32_16x16x32_bf16 v[26:29], v[170:173], v[210:213], v[26:29]
	v_mfma_f32_16x16x32_bf16 v[18:21], v[178:181], v[210:213], v[18:21]
	v_mfma_f32_16x16x32_bf16 v[10:13], v[170:173], v[218:221], v[10:13]
	v_mfma_f32_16x16x32_bf16 v[2:5], v[178:181], v[218:221], v[2:5]
	s_setprio 0
	s_barrier
	s_add_i32 s50, s50, 2
	s_add_u32 s20, s20, 0x100
	s_addc_u32 s21, s21, 0
	s_add_u32 s48, s48, 0x100
	s_addc_u32 s49, s49, 0
	s_cmp_gt_u32 s50, 13
	s_cbranch_scc0 .LBB0_684
	s_and_b64 vcc, exec, s[10:11]
	s_cbranch_vccz .LBB0_687
	s_barrier
